# attention: optimistic items, iterations after the first skip the per-tile max tree; end-of-item row-sum check re-runs an item in checked mode if needed
# speedup vs baseline: 1.0109x; 1.0109x over previous
.LBB0_877:
	s_or_b64 exec, exec, s[0:1]
	v_lshrrev_b32_e32 v244, 1, v254
	v_and_b32_e32 v244, 0x80, v244
	v_xor_b32_e32 v244, v244, v254
	v_mov_b32_e32 v1, v244
	s_waitcnt lgkmcnt(0)
	s_barrier
	s_cmp_lg_u32 0, -1
	v_lshrrev_b32_e32 v5, 2, v1
	v_lshrrev_b32_e32 v2, 5, v1
	v_lshlrev_b32_e32 v4, 2, v1
	v_and_b32_e32 v6, 2, v5
	v_and_or_b32 v4, v4, 12, v6
	v_xor_b32_e32 v6, v2, v5
	v_and_or_b32 v4, v6, 1, v4
	v_lshrrev_b32_e32 v6, 1, v1
	v_and_b32_e32 v0, 31, v1
	v_xor_b32_e32 v2, v2, v6
	v_lshlrev_b32_e32 v7, 7, v0
	v_lshlrev_b32_e32 v2, 4, v2
	v_lshlrev_b32_e32 v6, 3, v1
	v_bfe_u32 v3, v1, 5, 1
	v_and_or_b32 v2, v2, 16, v7
	v_and_b32_e32 v7, 0x60, v6
	v_bfe_u32 v8, v1, 2, 2
	v_and_b32_e32 v6, 8, v6
	s_cselect_b32 s0, 0, 0
	v_lshrrev_b32_e32 v9, 3, v1
	v_lshlrev_b32_e32 v12, 10, v3
	v_lshlrev_b32_e32 v13, 8, v8
	v_add_u32_e32 v6, s0, v6
	v_and_b32_e32 v10, 2, v9
	v_bfe_u32 v11, v1, 1, 1
	v_add3_u32 v6, v6, v12, v13
	v_or_b32_e32 v13, 2, v3
	v_lshlrev_b32_e32 v0, 8, v0
	v_bitop3_b32 v12, v10, v3, v11 bitop3:0x36
	v_bitop3_b32 v10, v10, v13, v11 bitop3:0x36
	v_lshl_or_b32 v198, v4, 4, v0
	v_lshlrev_b32_e32 v0, 4, v1
	v_lshlrev_b32_e32 v10, 4, v10
	s_movk_i32 s0, 0x800
	v_lshlrev_b32_e32 v8, 6, v8
	s_movk_i32 s16, 0x4000
	v_and_b32_e32 v0, 0x1f0, v0
	v_lshl_add_u32 v12, v12, 4, v6
	v_add3_u32 v6, v6, v10, s0
	v_xor_b32_e32 v10, 64, v8
	v_or3_b32 v199, v2, v7, s16
	v_lshl_or_b32 v2, v3, 9, v0
	v_mov_b32_e32 v0, 0
	v_add_u32_e32 v188, v12, v8
	v_add_u32_e32 v189, v6, v8
	v_add_u32_e32 v192, v12, v10
	v_add_u32_e32 v193, v6, v10
	v_xor_b32_e32 v10, 0x80, v8
	v_xor_b32_e32 v8, 0xc0, v8
	v_mov_b32_e32 v3, v0
	v_add_u32_e32 v196, v12, v8
	v_add_u32_e32 v197, v6, v8
	v_lshl_add_u64 v[162:163], s[36:37], 0, v[2:3]
	v_and_b32_e32 v2, 15, v1
	v_and_b32_e32 v5, 12, v5
	v_bfe_u32 v8, v1, 6, 2
	v_bitop3_b32 v2, v5, v2, v8 bitop3:0x36
	s_not_b32 s0, s2
	v_add_u32_e32 v3, 0x200, v1
	v_lshrrev_b32_e32 v4, 4, v1
	v_lshlrev_b32_e32 v2, 4, v2
	s_movk_i32 s7, 0x180
	s_add_i32 s17, s30, s0
	v_mad_u64_u32 v[164:165], s[0:1], v4, s7, v[2:3]
	v_bfe_u32 v7, v1, 4, 5
	v_lshrrev_b32_e32 v5, 4, v3
	s_mov_b32 s0, 0x1ffffe0
	v_add_u32_e32 v195, v6, v10
	s_movk_i32 s6, 0xc0
	v_ashrrev_i32_e32 v6, 6, v1
	v_ashrrev_i32_e32 v200, 8, v1
	v_and_or_b32 v5, v5, s0, v7
	v_xor_b32_e32 v1, v4, v1
	v_mad_u64_u32 v[166:167], s[0:1], v5, s7, v[2:3]
	v_mul_lo_u32 v5, v9, s6
	v_lshlrev_b32_e32 v1, 3, v1
	v_and_or_b32 v1, v1, 56, v5
	v_mov_b32_e32 v5, 0x100
	v_lshlrev_b32_e32 v4, 10, v6
	v_lshl_add_u32 v168, v1, 1, v5
	v_lshrrev_b32_e32 v1, 9, v3
	v_mul_u32_u24_e32 v1, 0x3000, v1
	v_mul_u32_u24_e32 v3, 0x180, v7
	v_add_u32_e32 v203, 0, v4
	s_mov_b32 s3, 0
	v_add_u32_e32 v194, v12, v10
	v_and_b32_e32 v201, 3, v6
	v_mov_b32_e32 v165, v0
	v_mov_b32_e32 v167, v0
	v_mov_b32_e32 v169, v0
	s_movk_i32 s36, 0x3000
	v_add3_u32 v170, v1, v3, v2
	s_movk_i32 s37, 0x1000
	s_movk_i32 s40, 0x2000
	v_add_u32_e32 v204, 0x2000, v203
	v_add_u32_e32 v205, 0x4000, v203
	s_mov_b64 s[0:1], 0x1dc06000
	s_mov_b32 s41, 0x8000
	s_mov_b64 s[6:7], 0x1dc0c000
	s_movk_i32 s44, 0xfe0
	s_movk_i32 s45, 0x2200
	s_mov_b32 s50, 0xc000
	s_mov_b32 s51, 0x10000
	s_mov_b32 s52, 0x14000
	s_mov_b32 s53, 0x18000
	v_mbcnt_hi_u32_b32 v191, -1, v186
	v_readfirstlane_b32 s74, v203
	v_readfirstlane_b32 s76, v244
	s_nop 0
	s_bfe_u32 s76, s76, 0x10007
	v_xor_b32_e32 v171, 0x20, v198
	v_xor_b32_e32 v174, 0x40, v198
	v_xor_b32_e32 v175, 0x60, v198
	v_xor_b32_e32 v176, 0x80, v198
	v_xor_b32_e32 v177, 0xa0, v198
	v_xor_b32_e32 v178, 0xc0, v198
	v_xor_b32_e32 v179, 0xe0, v198
	v_xor_b32_e32 v202, 0x20, v199
	v_xor_b32_e32 v207, 0x40, v199
	v_xor_b32_e32 v208, 0x60, v199
	v_mov_b32_e32 v1, 0x23ff8
	v_mov_b32_e32 v180, 0
	ds_write_b32 v1, v180
	s_mov_b32 s78, 0
	s_mov_b32 s54, 0
	s_branch .LBB0_879

.LBB0_883:
	s_add_i32 s57, s57, 2
	s_add_u32 s8, s8, 0xc000
	s_addc_u32 s9, s9, 0
	s_and_b64 vcc, exec, s[12:13]
	s_waitcnt vmcnt(0) lgkmcnt(0)
	s_barrier
	s_cbranch_vccnz .LBB0_893
	s_cmp_eq_u32 s78, 0
	s_cbranch_scc1 .Lu884

.Latt_common1:
	v_exp_f32_e32 v82, v82
	v_exp_f32_e32 v83, v83
	v_exp_f32_e32 v84, v84
	v_add_f32_e32 v173, v173, v82
	v_exp_f32_e32 v85, v85
	v_mov_b32_e32 v242, v83
	v_cvt_pk_bf16_f32 v82, v82, v83
	v_exp_f32_e32 v86, v86
	v_add_f32_e32 v173, v173, v84
	v_exp_f32_e32 v87, v87
	v_add_f32_e32 v242, v242, v85
	v_cvt_pk_bf16_f32 v83, v84, v85
	v_exp_f32_e32 v88, v88
	v_add_f32_e32 v173, v173, v86
	v_exp_f32_e32 v89, v89
	v_add_f32_e32 v242, v242, v87
	v_cvt_pk_bf16_f32 v84, v86, v87
	v_add_f32_e32 v173, v173, v88
	v_add_f32_e32 v242, v242, v89
	v_cvt_pk_bf16_f32 v85, v88, v89
	ds_read_b64_tr_b16 v[238:239], v188 offset:0x7000
	ds_read_b64_tr_b16 v[240:241], v189 offset:0x7000
	ds_read_b64_tr_b16 v[234:235], v192 offset:0x7000
	ds_read_b64_tr_b16 v[236:237], v193 offset:0x7000
	ds_read_b64_tr_b16 v[230:231], v194 offset:0x7000
	ds_read_b64_tr_b16 v[232:233], v195 offset:0x7000
	ds_read_b64_tr_b16 v[226:227], v196 offset:0x7000
	ds_read_b64_tr_b16 v[228:229], v197 offset:0x7000
	s_waitcnt lgkmcnt(8)
	v_mfma_f32_32x32x16_bf16 v[50:65], v[158:161], v[82:85], v[50:65]
	v_exp_f32_e32 v90, v90
	v_exp_f32_e32 v91, v91
	v_exp_f32_e32 v92, v92
	v_add_f32_e32 v173, v173, v90
	v_exp_f32_e32 v93, v93
	v_mfma_f32_32x32x16_bf16 v[34:49], v[154:157], v[82:85], v[34:49]
	v_add_f32_e32 v242, v242, v91
	v_cvt_pk_bf16_f32 v90, v90, v91
	v_exp_f32_e32 v94, v94
	v_add_f32_e32 v173, v173, v92
	v_exp_f32_e32 v95, v95
	v_mfma_f32_32x32x16_bf16 v[18:33], v[150:153], v[82:85], v[18:33]
	v_add_f32_e32 v242, v242, v93
	v_cvt_pk_bf16_f32 v91, v92, v93
	v_exp_f32_e32 v96, v96
	v_add_f32_e32 v173, v173, v94
	v_exp_f32_e32 v97, v97
	v_mfma_f32_32x32x16_bf16 v[2:17], v[146:149], v[82:85], v[2:17]
	v_add_f32_e32 v242, v242, v95
	v_cvt_pk_bf16_f32 v92, v94, v95
	v_add_f32_e32 v173, v173, v96
	v_add_f32_e32 v242, v242, v97
	v_cvt_pk_bf16_f32 v93, v96, v97
	ds_read_b64_tr_b16 v[158:159], v188 offset:0x8000
	ds_read_b64_tr_b16 v[160:161], v189 offset:0x8000
	ds_read_b64_tr_b16 v[154:155], v192 offset:0x8000
	ds_read_b64_tr_b16 v[156:157], v193 offset:0x8000
	ds_read_b64_tr_b16 v[150:151], v194 offset:0x8000
	ds_read_b64_tr_b16 v[152:153], v195 offset:0x8000
	ds_read_b64_tr_b16 v[146:147], v196 offset:0x8000
	ds_read_b64_tr_b16 v[148:149], v197 offset:0x8000
	s_waitcnt lgkmcnt(8)
	v_mfma_f32_32x32x16_bf16 v[50:65], v[238:241], v[90:93], v[50:65]
	v_exp_f32_e32 v66, v66
	v_exp_f32_e32 v67, v67
	v_exp_f32_e32 v68, v68
	v_add_f32_e32 v173, v173, v66
	v_exp_f32_e32 v69, v69
	v_mfma_f32_32x32x16_bf16 v[34:49], v[234:237], v[90:93], v[34:49]
	v_add_f32_e32 v242, v242, v67
	v_cvt_pk_bf16_f32 v66, v66, v67
	v_exp_f32_e32 v70, v70
	v_add_f32_e32 v173, v173, v68
	v_exp_f32_e32 v71, v71
	v_mfma_f32_32x32x16_bf16 v[18:33], v[230:233], v[90:93], v[18:33]
	v_add_f32_e32 v242, v242, v69
	v_cvt_pk_bf16_f32 v67, v68, v69
	v_exp_f32_e32 v72, v72
	v_add_f32_e32 v173, v173, v70
	v_exp_f32_e32 v73, v73
	v_mfma_f32_32x32x16_bf16 v[2:17], v[226:229], v[90:93], v[2:17]
	v_add_f32_e32 v242, v242, v71
	v_cvt_pk_bf16_f32 v68, v70, v71
	v_add_f32_e32 v173, v173, v72
	v_add_f32_e32 v242, v242, v73
	v_cvt_pk_bf16_f32 v69, v72, v73
	ds_read_b64_tr_b16 v[238:239], v188 offset:0x9000
	ds_read_b64_tr_b16 v[240:241], v189 offset:0x9000
	ds_read_b64_tr_b16 v[234:235], v192 offset:0x9000
	ds_read_b64_tr_b16 v[236:237], v193 offset:0x9000
	ds_read_b64_tr_b16 v[230:231], v194 offset:0x9000
	ds_read_b64_tr_b16 v[232:233], v195 offset:0x9000
	ds_read_b64_tr_b16 v[226:227], v196 offset:0x9000
	ds_read_b64_tr_b16 v[228:229], v197 offset:0x9000
	s_waitcnt lgkmcnt(8)
	v_mfma_f32_32x32x16_bf16 v[50:65], v[158:161], v[66:69], v[50:65]
	v_exp_f32_e32 v74, v74
	v_exp_f32_e32 v75, v75
	v_exp_f32_e32 v76, v76
	v_add_f32_e32 v173, v173, v74
	v_exp_f32_e32 v77, v77
	v_mfma_f32_32x32x16_bf16 v[34:49], v[154:157], v[66:69], v[34:49]
	v_add_f32_e32 v242, v242, v75
	v_cvt_pk_bf16_f32 v74, v74, v75
	v_exp_f32_e32 v78, v78
	v_add_f32_e32 v173, v173, v76
	v_exp_f32_e32 v79, v79
	v_mfma_f32_32x32x16_bf16 v[18:33], v[150:153], v[66:69], v[18:33]
	v_add_f32_e32 v242, v242, v77
	v_cvt_pk_bf16_f32 v75, v76, v77
	v_exp_f32_e32 v80, v80
	v_add_f32_e32 v173, v173, v78
	v_exp_f32_e32 v81, v81
	v_mfma_f32_32x32x16_bf16 v[2:17], v[146:149], v[66:69], v[2:17]
	v_add_f32_e32 v242, v242, v79
	v_cvt_pk_bf16_f32 v76, v78, v79
	v_add_f32_e32 v173, v173, v80
	v_add_f32_e32 v242, v242, v81
	v_cvt_pk_bf16_f32 v77, v80, v81
	s_waitcnt lgkmcnt(0)
	v_add_f32_e32 v173, v173, v242
	v_mfma_f32_32x32x16_bf16 v[50:65], v[238:241], v[74:77], v[50:65]
	v_mfma_f32_32x32x16_bf16 v[34:49], v[234:237], v[74:77], v[34:49]
	v_mfma_f32_32x32x16_bf16 v[18:33], v[230:233], v[74:77], v[18:33]
	v_mfma_f32_32x32x16_bf16 v[2:17], v[226:229], v[74:77], v[2:17]
	s_branch .LBB0_883
.Lu883:
	s_add_i32 s57, s57, 2
	s_add_u32 s8, s8, 0xc000
	s_addc_u32 s9, s9, 0
	s_and_b64 vcc, exec, s[12:13]
	s_waitcnt vmcnt(0) lgkmcnt(0)
	s_barrier
	s_cbranch_vccnz .LBB0_893
.Lu884:
	s_add_u32 s72, s8, s0
	s_addc_u32 s73, s9, s1
	s_add_u32 m0, s74, 0x6000
	s_nop 0
	global_load_lds_dwordx4 v164, s[72:73]
	s_add_u32 m0, s74, 0x8000
	s_nop 0
	global_load_lds_dwordx4 v170, s[72:73]
	s_add_u32 m0, s74, 0xa000
	s_nop 0
	global_load_lds_dwordx4 v168, s[72:73]
	s_cmp_gt_u32 s57, s75
	s_cbranch_scc1 .Lu888
	ds_read_b128 v[146:149], v198
	ds_read_b128 v[150:153], v198 offset:8192
	ds_read_b128 v[246:249], v171
	ds_read_b128 v[250:253], v171 offset:8192
	ds_read_b128 v[180:183], v174
	ds_read_b128 v[184:187], v174 offset:8192
	s_waitcnt lgkmcnt(4)
	v_mfma_f32_32x32x16_bf16 v[82:97], v[146:149], v[98:101], v[210:225]
	v_mfma_f32_32x32x16_bf16 v[66:81], v[150:153], v[98:101], v[210:225]
	ds_read_b128 v[146:149], v175
	ds_read_b128 v[150:153], v175 offset:8192
	s_waitcnt lgkmcnt(4)
	v_mfma_f32_32x32x16_bf16 v[82:97], v[246:249], v[102:105], v[82:97]
	v_mfma_f32_32x32x16_bf16 v[66:81], v[250:253], v[102:105], v[66:81]
	ds_read_b128 v[246:249], v176
	ds_read_b128 v[250:253], v176 offset:8192
	s_waitcnt lgkmcnt(4)
	v_mfma_f32_32x32x16_bf16 v[82:97], v[180:183], v[106:109], v[82:97]
	v_mfma_f32_32x32x16_bf16 v[66:81], v[184:187], v[106:109], v[66:81]
	ds_read_b128 v[180:183], v177
	ds_read_b128 v[184:187], v177 offset:8192
	s_waitcnt lgkmcnt(4)
	v_mfma_f32_32x32x16_bf16 v[82:97], v[146:149], v[110:113], v[82:97]
	v_mfma_f32_32x32x16_bf16 v[66:81], v[150:153], v[110:113], v[66:81]
	ds_read_b128 v[146:149], v178
	ds_read_b128 v[150:153], v178 offset:8192
	s_waitcnt lgkmcnt(4)
	v_mfma_f32_32x32x16_bf16 v[82:97], v[246:249], v[122:125], v[82:97]
	v_mfma_f32_32x32x16_bf16 v[66:81], v[250:253], v[122:125], v[66:81]
	ds_read_b128 v[246:249], v179
	ds_read_b128 v[250:253], v179 offset:8192
	s_waitcnt lgkmcnt(4)
	v_mfma_f32_32x32x16_bf16 v[82:97], v[180:183], v[114:117], v[82:97]
	v_mfma_f32_32x32x16_bf16 v[66:81], v[184:187], v[114:117], v[66:81]
	ds_read_b128 v[180:183], v199
	ds_read_b128 v[184:187], v199 offset:4096
	s_waitcnt lgkmcnt(4)
	v_mfma_f32_32x32x16_bf16 v[82:97], v[146:149], v[118:121], v[82:97]
	v_mfma_f32_32x32x16_bf16 v[66:81], v[150:153], v[118:121], v[66:81]
	ds_read_b128 v[146:149], v202
	ds_read_b128 v[150:153], v202 offset:4096
	s_waitcnt lgkmcnt(4)
	v_mfma_f32_32x32x16_bf16 v[82:97], v[246:249], v[126:129], v[82:97]
	v_mfma_f32_32x32x16_bf16 v[66:81], v[250:253], v[126:129], v[66:81]
	ds_read_b128 v[246:249], v207
	ds_read_b128 v[250:253], v207 offset:4096
	s_waitcnt lgkmcnt(4)
	v_mfma_f32_32x32x16_bf16 v[82:97], v[180:183], v[130:133], v[82:97]
	v_mfma_f32_32x32x16_bf16 v[66:81], v[184:187], v[130:133], v[66:81]
	ds_read_b128 v[180:183], v208
	ds_read_b128 v[184:187], v208 offset:4096
	s_waitcnt lgkmcnt(4)
	v_mfma_f32_32x32x16_bf16 v[82:97], v[146:149], v[134:137], v[82:97]
	v_mfma_f32_32x32x16_bf16 v[66:81], v[150:153], v[134:137], v[66:81]
	s_waitcnt lgkmcnt(2)
	v_mfma_f32_32x32x16_bf16 v[82:97], v[246:249], v[138:141], v[82:97]
	v_mfma_f32_32x32x16_bf16 v[66:81], v[250:253], v[138:141], v[66:81]
	s_waitcnt lgkmcnt(0)
	v_mfma_f32_32x32x16_bf16 v[66:81], v[184:187], v[142:145], v[66:81]
	v_mfma_f32_32x32x16_bf16 v[82:97], v[180:183], v[142:145], v[82:97]
	ds_read_b64_tr_b16 v[158:159], v188 offset:0
	ds_read_b64_tr_b16 v[160:161], v189 offset:0
	ds_read_b64_tr_b16 v[154:155], v192 offset:0
	ds_read_b64_tr_b16 v[156:157], v193 offset:0
	ds_read_b64_tr_b16 v[150:151], v194 offset:0
	ds_read_b64_tr_b16 v[152:153], v195 offset:0
	ds_read_b64_tr_b16 v[146:147], v196 offset:0
	ds_read_b64_tr_b16 v[148:149], v197 offset:0
	s_nop 2
	v_exp_f32_e32 v82, v82
	v_exp_f32_e32 v83, v83
	v_exp_f32_e32 v84, v84
	v_add_f32_e32 v173, v173, v82
	v_exp_f32_e32 v85, v85
	v_mov_b32_e32 v242, v83
	v_cvt_pk_bf16_f32 v82, v82, v83
	v_exp_f32_e32 v86, v86
	v_add_f32_e32 v173, v173, v84
	v_exp_f32_e32 v87, v87
	v_add_f32_e32 v242, v242, v85
	v_cvt_pk_bf16_f32 v83, v84, v85
	v_exp_f32_e32 v88, v88
	v_add_f32_e32 v173, v173, v86
	v_exp_f32_e32 v89, v89
	v_add_f32_e32 v242, v242, v87
	v_cvt_pk_bf16_f32 v84, v86, v87
	v_add_f32_e32 v173, v173, v88
	v_add_f32_e32 v242, v242, v89
	v_cvt_pk_bf16_f32 v85, v88, v89
	ds_read_b64_tr_b16 v[238:239], v188 offset:0x1000
	ds_read_b64_tr_b16 v[240:241], v189 offset:0x1000
	ds_read_b64_tr_b16 v[234:235], v192 offset:0x1000
	ds_read_b64_tr_b16 v[236:237], v193 offset:0x1000
	ds_read_b64_tr_b16 v[230:231], v194 offset:0x1000
	ds_read_b64_tr_b16 v[232:233], v195 offset:0x1000
	ds_read_b64_tr_b16 v[226:227], v196 offset:0x1000
	ds_read_b64_tr_b16 v[228:229], v197 offset:0x1000
	s_waitcnt lgkmcnt(8)
	v_mfma_f32_32x32x16_bf16 v[50:65], v[158:161], v[82:85], v[50:65]
	v_exp_f32_e32 v90, v90
	v_exp_f32_e32 v91, v91
	v_exp_f32_e32 v92, v92
	v_add_f32_e32 v173, v173, v90
	v_exp_f32_e32 v93, v93
	v_mfma_f32_32x32x16_bf16 v[34:49], v[154:157], v[82:85], v[34:49]
	v_add_f32_e32 v242, v242, v91
	v_cvt_pk_bf16_f32 v90, v90, v91
	v_exp_f32_e32 v94, v94
	v_add_f32_e32 v173, v173, v92
	v_exp_f32_e32 v95, v95
	v_mfma_f32_32x32x16_bf16 v[18:33], v[150:153], v[82:85], v[18:33]
	v_add_f32_e32 v242, v242, v93
	v_cvt_pk_bf16_f32 v91, v92, v93
	v_exp_f32_e32 v96, v96
	v_add_f32_e32 v173, v173, v94
	v_exp_f32_e32 v97, v97
	v_mfma_f32_32x32x16_bf16 v[2:17], v[146:149], v[82:85], v[2:17]
	v_add_f32_e32 v242, v242, v95
	v_cvt_pk_bf16_f32 v92, v94, v95
	v_add_f32_e32 v173, v173, v96
	v_add_f32_e32 v242, v242, v97
	v_cvt_pk_bf16_f32 v93, v96, v97
	ds_read_b64_tr_b16 v[158:159], v188 offset:0x2000
	ds_read_b64_tr_b16 v[160:161], v189 offset:0x2000
	ds_read_b64_tr_b16 v[154:155], v192 offset:0x2000
	ds_read_b64_tr_b16 v[156:157], v193 offset:0x2000
	ds_read_b64_tr_b16 v[150:151], v194 offset:0x2000
	ds_read_b64_tr_b16 v[152:153], v195 offset:0x2000
	ds_read_b64_tr_b16 v[146:147], v196 offset:0x2000
	ds_read_b64_tr_b16 v[148:149], v197 offset:0x2000
	s_waitcnt lgkmcnt(8)
	v_mfma_f32_32x32x16_bf16 v[50:65], v[238:241], v[90:93], v[50:65]
	v_exp_f32_e32 v66, v66
	v_exp_f32_e32 v67, v67
	v_exp_f32_e32 v68, v68
	v_add_f32_e32 v173, v173, v66
	v_exp_f32_e32 v69, v69
	v_mfma_f32_32x32x16_bf16 v[34:49], v[234:237], v[90:93], v[34:49]
	v_add_f32_e32 v242, v242, v67
	v_cvt_pk_bf16_f32 v66, v66, v67
	v_exp_f32_e32 v70, v70
	v_add_f32_e32 v173, v173, v68
	v_exp_f32_e32 v71, v71
	v_mfma_f32_32x32x16_bf16 v[18:33], v[230:233], v[90:93], v[18:33]
	v_add_f32_e32 v242, v242, v69
	v_cvt_pk_bf16_f32 v67, v68, v69
	v_exp_f32_e32 v72, v72
	v_add_f32_e32 v173, v173, v70
	v_exp_f32_e32 v73, v73
	v_mfma_f32_32x32x16_bf16 v[2:17], v[226:229], v[90:93], v[2:17]
	v_add_f32_e32 v242, v242, v71
	v_cvt_pk_bf16_f32 v68, v70, v71
	v_add_f32_e32 v173, v173, v72
	v_add_f32_e32 v242, v242, v73
	v_cvt_pk_bf16_f32 v69, v72, v73
	ds_read_b64_tr_b16 v[238:239], v188 offset:0x3000
	ds_read_b64_tr_b16 v[240:241], v189 offset:0x3000
	ds_read_b64_tr_b16 v[234:235], v192 offset:0x3000
	ds_read_b64_tr_b16 v[236:237], v193 offset:0x3000
	ds_read_b64_tr_b16 v[230:231], v194 offset:0x3000
	ds_read_b64_tr_b16 v[232:233], v195 offset:0x3000
	ds_read_b64_tr_b16 v[226:227], v196 offset:0x3000
	ds_read_b64_tr_b16 v[228:229], v197 offset:0x3000
	s_waitcnt lgkmcnt(8)
	v_mfma_f32_32x32x16_bf16 v[50:65], v[158:161], v[66:69], v[50:65]
	v_exp_f32_e32 v74, v74
	v_exp_f32_e32 v75, v75
	v_exp_f32_e32 v76, v76
	v_add_f32_e32 v173, v173, v74
	v_exp_f32_e32 v77, v77
	v_mfma_f32_32x32x16_bf16 v[34:49], v[154:157], v[66:69], v[34:49]
	v_add_f32_e32 v242, v242, v75
	v_cvt_pk_bf16_f32 v74, v74, v75
	v_exp_f32_e32 v78, v78
	v_add_f32_e32 v173, v173, v76
	v_exp_f32_e32 v79, v79
	v_mfma_f32_32x32x16_bf16 v[18:33], v[150:153], v[66:69], v[18:33]
	v_add_f32_e32 v242, v242, v77
	v_cvt_pk_bf16_f32 v75, v76, v77
	v_exp_f32_e32 v80, v80
	v_add_f32_e32 v173, v173, v78
	v_exp_f32_e32 v81, v81
	v_mfma_f32_32x32x16_bf16 v[2:17], v[146:149], v[66:69], v[2:17]
	v_add_f32_e32 v242, v242, v79
	v_cvt_pk_bf16_f32 v76, v78, v79
	v_add_f32_e32 v173, v173, v80
	v_add_f32_e32 v242, v242, v81
	v_cvt_pk_bf16_f32 v77, v80, v81
	s_waitcnt lgkmcnt(0)
	v_add_f32_e32 v173, v173, v242
	v_mfma_f32_32x32x16_bf16 v[50:65], v[238:241], v[74:77], v[50:65]
	v_mfma_f32_32x32x16_bf16 v[34:49], v[234:237], v[74:77], v[34:49]
	v_mfma_f32_32x32x16_bf16 v[18:33], v[230:233], v[74:77], v[18:33]
	v_mfma_f32_32x32x16_bf16 v[2:17], v[226:229], v[74:77], v[2:17]

.Lu890:
	s_cmp_ge_u32 s57, s75
	s_cbranch_scc1 .Lu883
	ds_read_b128 v[146:149], v198 offset:24576
	ds_read_b128 v[150:153], v198 offset:32768
	ds_read_b128 v[246:249], v171 offset:24576
	ds_read_b128 v[250:253], v171 offset:32768
	ds_read_b128 v[180:183], v174 offset:24576
	ds_read_b128 v[184:187], v174 offset:32768
	s_waitcnt lgkmcnt(4)
	v_mfma_f32_32x32x16_bf16 v[82:97], v[146:149], v[98:101], v[210:225]
	v_mfma_f32_32x32x16_bf16 v[66:81], v[150:153], v[98:101], v[210:225]
	ds_read_b128 v[146:149], v175 offset:24576
	ds_read_b128 v[150:153], v175 offset:32768
	s_waitcnt lgkmcnt(4)
	v_mfma_f32_32x32x16_bf16 v[82:97], v[246:249], v[102:105], v[82:97]
	v_mfma_f32_32x32x16_bf16 v[66:81], v[250:253], v[102:105], v[66:81]
	ds_read_b128 v[246:249], v176 offset:24576
	ds_read_b128 v[250:253], v176 offset:32768
	s_waitcnt lgkmcnt(4)
	v_mfma_f32_32x32x16_bf16 v[82:97], v[180:183], v[106:109], v[82:97]
	v_mfma_f32_32x32x16_bf16 v[66:81], v[184:187], v[106:109], v[66:81]
	ds_read_b128 v[180:183], v177 offset:24576
	ds_read_b128 v[184:187], v177 offset:32768
	s_waitcnt lgkmcnt(4)
	v_mfma_f32_32x32x16_bf16 v[82:97], v[146:149], v[110:113], v[82:97]
	v_mfma_f32_32x32x16_bf16 v[66:81], v[150:153], v[110:113], v[66:81]
	ds_read_b128 v[146:149], v178 offset:24576
	ds_read_b128 v[150:153], v178 offset:32768
	s_waitcnt lgkmcnt(4)
	v_mfma_f32_32x32x16_bf16 v[82:97], v[246:249], v[122:125], v[82:97]
	v_mfma_f32_32x32x16_bf16 v[66:81], v[250:253], v[122:125], v[66:81]
	ds_read_b128 v[246:249], v179 offset:24576
	ds_read_b128 v[250:253], v179 offset:32768
	s_waitcnt lgkmcnt(4)
	v_mfma_f32_32x32x16_bf16 v[82:97], v[180:183], v[114:117], v[82:97]
	v_mfma_f32_32x32x16_bf16 v[66:81], v[184:187], v[114:117], v[66:81]
	ds_read_b128 v[180:183], v199 offset:24576
	ds_read_b128 v[184:187], v199 offset:28672
	s_waitcnt lgkmcnt(4)
	v_mfma_f32_32x32x16_bf16 v[82:97], v[146:149], v[118:121], v[82:97]
	v_mfma_f32_32x32x16_bf16 v[66:81], v[150:153], v[118:121], v[66:81]
	ds_read_b128 v[146:149], v202 offset:24576
	ds_read_b128 v[150:153], v202 offset:28672
	s_waitcnt lgkmcnt(4)
	v_mfma_f32_32x32x16_bf16 v[82:97], v[246:249], v[126:129], v[82:97]
	v_mfma_f32_32x32x16_bf16 v[66:81], v[250:253], v[126:129], v[66:81]
	ds_read_b128 v[246:249], v207 offset:24576
	ds_read_b128 v[250:253], v207 offset:28672
	s_waitcnt lgkmcnt(4)
	v_mfma_f32_32x32x16_bf16 v[82:97], v[180:183], v[130:133], v[82:97]
	v_mfma_f32_32x32x16_bf16 v[66:81], v[184:187], v[130:133], v[66:81]
	ds_read_b128 v[180:183], v208 offset:24576
	ds_read_b128 v[184:187], v208 offset:28672
	s_waitcnt lgkmcnt(4)
	v_mfma_f32_32x32x16_bf16 v[82:97], v[146:149], v[134:137], v[82:97]
	v_mfma_f32_32x32x16_bf16 v[66:81], v[150:153], v[134:137], v[66:81]
	s_waitcnt lgkmcnt(2)
	v_mfma_f32_32x32x16_bf16 v[82:97], v[246:249], v[138:141], v[82:97]
	v_mfma_f32_32x32x16_bf16 v[66:81], v[250:253], v[138:141], v[66:81]
	s_waitcnt lgkmcnt(0)
	v_mfma_f32_32x32x16_bf16 v[66:81], v[184:187], v[142:145], v[66:81]
	v_mfma_f32_32x32x16_bf16 v[82:97], v[180:183], v[142:145], v[82:97]
	ds_read_b64_tr_b16 v[158:159], v188 offset:0x6000
	ds_read_b64_tr_b16 v[160:161], v189 offset:0x6000
	ds_read_b64_tr_b16 v[154:155], v192 offset:0x6000
	ds_read_b64_tr_b16 v[156:157], v193 offset:0x6000
	ds_read_b64_tr_b16 v[150:151], v194 offset:0x6000
	ds_read_b64_tr_b16 v[152:153], v195 offset:0x6000
	ds_read_b64_tr_b16 v[146:147], v196 offset:0x6000
	ds_read_b64_tr_b16 v[148:149], v197 offset:0x6000
	s_nop 2
	v_exp_f32_e32 v82, v82
	v_exp_f32_e32 v83, v83
	v_exp_f32_e32 v84, v84
	v_add_f32_e32 v173, v173, v82
	v_exp_f32_e32 v85, v85
	v_mov_b32_e32 v242, v83
	v_cvt_pk_bf16_f32 v82, v82, v83
	v_exp_f32_e32 v86, v86
	v_add_f32_e32 v173, v173, v84
	v_exp_f32_e32 v87, v87
	v_add_f32_e32 v242, v242, v85
	v_cvt_pk_bf16_f32 v83, v84, v85
	v_exp_f32_e32 v88, v88
	v_add_f32_e32 v173, v173, v86
	v_exp_f32_e32 v89, v89
	v_add_f32_e32 v242, v242, v87
	v_cvt_pk_bf16_f32 v84, v86, v87
	v_add_f32_e32 v173, v173, v88
	v_add_f32_e32 v242, v242, v89
	v_cvt_pk_bf16_f32 v85, v88, v89
	ds_read_b64_tr_b16 v[238:239], v188 offset:0x7000
	ds_read_b64_tr_b16 v[240:241], v189 offset:0x7000
	ds_read_b64_tr_b16 v[234:235], v192 offset:0x7000
	ds_read_b64_tr_b16 v[236:237], v193 offset:0x7000
	ds_read_b64_tr_b16 v[230:231], v194 offset:0x7000
	ds_read_b64_tr_b16 v[232:233], v195 offset:0x7000
	ds_read_b64_tr_b16 v[226:227], v196 offset:0x7000
	ds_read_b64_tr_b16 v[228:229], v197 offset:0x7000
	s_waitcnt lgkmcnt(8)
	v_mfma_f32_32x32x16_bf16 v[50:65], v[158:161], v[82:85], v[50:65]
	v_exp_f32_e32 v90, v90
	v_exp_f32_e32 v91, v91
	v_exp_f32_e32 v92, v92
	v_add_f32_e32 v173, v173, v90
	v_exp_f32_e32 v93, v93
	v_mfma_f32_32x32x16_bf16 v[34:49], v[154:157], v[82:85], v[34:49]
	v_add_f32_e32 v242, v242, v91
	v_cvt_pk_bf16_f32 v90, v90, v91
	v_exp_f32_e32 v94, v94
	v_add_f32_e32 v173, v173, v92
	v_exp_f32_e32 v95, v95
	v_mfma_f32_32x32x16_bf16 v[18:33], v[150:153], v[82:85], v[18:33]
	v_add_f32_e32 v242, v242, v93
	v_cvt_pk_bf16_f32 v91, v92, v93
	v_exp_f32_e32 v96, v96
	v_add_f32_e32 v173, v173, v94
	v_exp_f32_e32 v97, v97
	v_mfma_f32_32x32x16_bf16 v[2:17], v[146:149], v[82:85], v[2:17]
	v_add_f32_e32 v242, v242, v95
	v_cvt_pk_bf16_f32 v92, v94, v95
	v_add_f32_e32 v173, v173, v96
	v_add_f32_e32 v242, v242, v97
	v_cvt_pk_bf16_f32 v93, v96, v97
	ds_read_b64_tr_b16 v[158:159], v188 offset:0x8000
	ds_read_b64_tr_b16 v[160:161], v189 offset:0x8000
	ds_read_b64_tr_b16 v[154:155], v192 offset:0x8000
	ds_read_b64_tr_b16 v[156:157], v193 offset:0x8000
	ds_read_b64_tr_b16 v[150:151], v194 offset:0x8000
	ds_read_b64_tr_b16 v[152:153], v195 offset:0x8000
	ds_read_b64_tr_b16 v[146:147], v196 offset:0x8000
	ds_read_b64_tr_b16 v[148:149], v197 offset:0x8000
	s_waitcnt lgkmcnt(8)
	v_mfma_f32_32x32x16_bf16 v[50:65], v[238:241], v[90:93], v[50:65]
	v_exp_f32_e32 v66, v66
	v_exp_f32_e32 v67, v67
	v_exp_f32_e32 v68, v68
	v_add_f32_e32 v173, v173, v66
	v_exp_f32_e32 v69, v69
	v_mfma_f32_32x32x16_bf16 v[34:49], v[234:237], v[90:93], v[34:49]
	v_add_f32_e32 v242, v242, v67
	v_cvt_pk_bf16_f32 v66, v66, v67
	v_exp_f32_e32 v70, v70
	v_add_f32_e32 v173, v173, v68
	v_exp_f32_e32 v71, v71
	v_mfma_f32_32x32x16_bf16 v[18:33], v[230:233], v[90:93], v[18:33]
	v_add_f32_e32 v242, v242, v69
	v_cvt_pk_bf16_f32 v67, v68, v69
	v_exp_f32_e32 v72, v72
	v_add_f32_e32 v173, v173, v70
	v_exp_f32_e32 v73, v73
	v_mfma_f32_32x32x16_bf16 v[2:17], v[226:229], v[90:93], v[2:17]
	v_add_f32_e32 v242, v242, v71
	v_cvt_pk_bf16_f32 v68, v70, v71
	v_add_f32_e32 v173, v173, v72
	v_add_f32_e32 v242, v242, v73
	v_cvt_pk_bf16_f32 v69, v72, v73
	ds_read_b64_tr_b16 v[238:239], v188 offset:0x9000
	ds_read_b64_tr_b16 v[240:241], v189 offset:0x9000
	ds_read_b64_tr_b16 v[234:235], v192 offset:0x9000
	ds_read_b64_tr_b16 v[236:237], v193 offset:0x9000
	ds_read_b64_tr_b16 v[230:231], v194 offset:0x9000
	ds_read_b64_tr_b16 v[232:233], v195 offset:0x9000
	ds_read_b64_tr_b16 v[226:227], v196 offset:0x9000
	ds_read_b64_tr_b16 v[228:229], v197 offset:0x9000
	s_waitcnt lgkmcnt(8)
	v_mfma_f32_32x32x16_bf16 v[50:65], v[158:161], v[66:69], v[50:65]
	v_exp_f32_e32 v74, v74
	v_exp_f32_e32 v75, v75
	v_exp_f32_e32 v76, v76
	v_add_f32_e32 v173, v173, v74
	v_exp_f32_e32 v77, v77
	v_mfma_f32_32x32x16_bf16 v[34:49], v[154:157], v[66:69], v[34:49]
	v_add_f32_e32 v242, v242, v75
	v_cvt_pk_bf16_f32 v74, v74, v75
	v_exp_f32_e32 v78, v78
	v_add_f32_e32 v173, v173, v76
	v_exp_f32_e32 v79, v79
	v_mfma_f32_32x32x16_bf16 v[18:33], v[150:153], v[66:69], v[18:33]
	v_add_f32_e32 v242, v242, v77
	v_cvt_pk_bf16_f32 v75, v76, v77
	v_exp_f32_e32 v80, v80
	v_add_f32_e32 v173, v173, v78
	v_exp_f32_e32 v81, v81
	v_mfma_f32_32x32x16_bf16 v[2:17], v[146:149], v[66:69], v[2:17]
	v_add_f32_e32 v242, v242, v79
	v_cvt_pk_bf16_f32 v76, v78, v79
	v_add_f32_e32 v173, v173, v80
	v_add_f32_e32 v242, v242, v81
	v_cvt_pk_bf16_f32 v77, v80, v81
	s_waitcnt lgkmcnt(0)
	v_add_f32_e32 v173, v173, v242
	v_mfma_f32_32x32x16_bf16 v[50:65], v[238:241], v[74:77], v[50:65]
	v_mfma_f32_32x32x16_bf16 v[34:49], v[234:237], v[74:77], v[34:49]
	v_mfma_f32_32x32x16_bf16 v[18:33], v[230:233], v[74:77], v[18:33]
	v_mfma_f32_32x32x16_bf16 v[2:17], v[226:229], v[74:77], v[2:17]
	s_branch .Lu883
.LBB0_893:
	s_cmp_lg_u32 s78, 0
	s_cbranch_scc1 .Lopt_done
	v_cmp_ngt_f32_e32 vcc, 0x71800000, v173
	s_cmp_eq_u64 vcc, 0
	s_cbranch_scc1 .Lopt_vote
	v_mov_b32_e32 v1, 0x23ff8
	v_mov_b32_e32 v180, 1
	ds_write_b32 v1, v180
.Lopt_vote:
	s_waitcnt lgkmcnt(0)
	s_barrier
	v_mov_b32_e32 v1, 0x23ff8
	ds_read_b32 v180, v1
	s_waitcnt lgkmcnt(0)
	v_readfirstlane_b32 s79, v180
	s_cmp_eq_u32 s79, 0
	s_cbranch_scc1 .Lopt_done
	s_barrier
	v_mov_b32_e32 v180, 0
	ds_write_b32 v1, v180
	s_waitcnt lgkmcnt(0)
	s_mov_b32 s78, 1
	s_branch .LBB0_879
.Lopt_done:
	s_mov_b32 s78, 0
	v_mov_b32_e32 v1, v244
	v_lshlrev_b32_e32 v98, 5, v206
	v_bfe_u32 v157, v1, 5, 1
	v_and_b32_e32 v156, 31, v1
	v_lshlrev_b32_e32 v66, 9, v157
	v_mov_b32_e32 v67, v0
	v_lshl_add_u64 v[66:67], s[38:39], 0, v[66:67]
	v_lshlrev_b32_e32 v68, 4, v156
	v_mov_b32_e32 v69, v0
	v_ashrrev_i32_e32 v99, 31, v98
	v_lshl_add_u64 v[100:101], v[66:67], 0, v[68:69]
	v_lshlrev_b64 v[66:67], 10, v[98:99]
	v_lshl_add_u64 v[74:75], v[100:101], 0, v[66:67]
	global_load_dwordx4 v[66:69], v[74:75], off
	v_or_b32_e32 v70, 8, v98
	v_ashrrev_i32_e32 v71, 31, v70
	v_lshlrev_b64 v[70:71], 10, v[70:71]
	v_lshl_add_u64 v[76:77], v[100:101], 0, v[70:71]
	global_load_dwordx4 v[70:73], v[76:77], off
	global_load_dwordx4 v[102:105], v[74:75], off offset:1024
	global_load_dwordx4 v[106:109], v[76:77], off offset:1024
	global_load_dwordx4 v[110:113], v[74:75], off offset:2048
	global_load_dwordx4 v[114:117], v[76:77], off offset:2048
	global_load_dwordx4 v[118:121], v[74:75], off offset:3072
	v_and_b32_e32 v79, 64, v191
	v_xor_b32_e32 v78, 32, v191
	v_add_u32_e32 v79, 64, v79
	v_cmp_lt_i32_e32 vcc, v78, v79
	global_load_dwordx4 v[122:125], v[76:77], off offset:3072
	v_ashrrev_i32_e32 v158, 6, v1
	v_cndmask_b32_e32 v78, v191, v78, vcc
	v_lshlrev_b32_e32 v78, 2, v78
	ds_bpermute_b32 v78, v78, v173
	v_add_co_u32_e32 v134, vcc, s37, v74
	v_bfe_u32 v160, v1, 4, 2
	s_nop 0
	v_addc_co_u32_e32 v135, vcc, 0, v75, vcc
	s_waitcnt lgkmcnt(0)
	v_add_f32_e32 v74, v173, v78
	v_div_scale_f32 v75, s[8:9], v74, v74, 1.0
	v_add_co_u32_e32 v136, vcc, s37, v76
	global_load_dwordx4 v[126:129], v[134:135], off
	v_rcp_f32_e32 v76, v75
	v_addc_co_u32_e32 v137, vcc, 0, v77, vcc
	v_div_scale_f32 v77, vcc, 1.0, v74, 1.0
	v_fma_f32 v78, -v75, v76, 1.0
	v_fmac_f32_e32 v76, v78, v76
	v_mul_f32_e32 v78, v77, v76
	v_fma_f32 v79, -v75, v78, v77
	v_fmac_f32_e32 v78, v79, v76
	v_fma_f32 v75, -v75, v78, v77
	v_div_fmas_f32 v75, v75, v76, v78
	v_div_fixup_f32 v138, v75, v74, 1.0
	v_pk_mul_f32 v[50:51], v[50:51], v[138:139] op_sel_hi:[1,0]
	v_pk_mul_f32 v[52:53], v[52:53], v[138:139] op_sel_hi:[1,0]
	v_pk_mul_f32 v[54:55], v[54:55], v[138:139] op_sel_hi:[1,0]
	v_pk_mul_f32 v[56:57], v[56:57], v[138:139] op_sel_hi:[1,0]
	v_cvt_pk_bf16_f32 v50, v50, v51
	v_cvt_pk_bf16_f32 v51, v52, v53
	v_cvt_pk_bf16_f32 v52, v54, v55
	v_cvt_pk_bf16_f32 v53, v56, v57
	global_load_dwordx4 v[54:57], v[136:137], off
	global_load_dwordx4 v[130:133], v[134:135], off offset:1024
	v_pk_mul_f32 v[58:59], v[58:59], v[138:139] op_sel_hi:[1,0]
	v_pk_mul_f32 v[60:61], v[60:61], v[138:139] op_sel_hi:[1,0]
	v_pk_mul_f32 v[62:63], v[62:63], v[138:139] op_sel_hi:[1,0]
	v_pk_mul_f32 v[64:65], v[64:65], v[138:139] op_sel_hi:[1,0]
	v_cvt_pk_bf16_f32 v58, v58, v59
	v_cvt_pk_bf16_f32 v59, v60, v61
	v_cvt_pk_bf16_f32 v60, v62, v63
	v_cvt_pk_bf16_f32 v61, v64, v65
	v_pk_mul_f32 v[34:35], v[34:35], v[138:139] op_sel_hi:[1,0]
	v_pk_mul_f32 v[36:37], v[36:37], v[138:139] op_sel_hi:[1,0]
	v_pk_mul_f32 v[38:39], v[38:39], v[138:139] op_sel_hi:[1,0]
	v_pk_mul_f32 v[40:41], v[40:41], v[138:139] op_sel_hi:[1,0]
	v_pk_mul_f32 v[42:43], v[42:43], v[138:139] op_sel_hi:[1,0]
	v_pk_mul_f32 v[44:45], v[44:45], v[138:139] op_sel_hi:[1,0]
	v_pk_mul_f32 v[46:47], v[46:47], v[138:139] op_sel_hi:[1,0]
	v_pk_mul_f32 v[48:49], v[48:49], v[138:139] op_sel_hi:[1,0]
	v_pk_mul_f32 v[18:19], v[18:19], v[138:139] op_sel_hi:[1,0]
	v_pk_mul_f32 v[20:21], v[20:21], v[138:139] op_sel_hi:[1,0]
	v_pk_mul_f32 v[22:23], v[22:23], v[138:139] op_sel_hi:[1,0]
	v_pk_mul_f32 v[24:25], v[24:25], v[138:139] op_sel_hi:[1,0]
	v_pk_mul_f32 v[26:27], v[26:27], v[138:139] op_sel_hi:[1,0]
	v_pk_mul_f32 v[28:29], v[28:29], v[138:139] op_sel_hi:[1,0]
	v_pk_mul_f32 v[30:31], v[30:31], v[138:139] op_sel_hi:[1,0]
	v_pk_mul_f32 v[32:33], v[32:33], v[138:139] op_sel_hi:[1,0]
	v_pk_mul_f32 v[2:3], v[2:3], v[138:139] op_sel_hi:[1,0]
	v_pk_mul_f32 v[4:5], v[4:5], v[138:139] op_sel_hi:[1,0]
	s_waitcnt vmcnt(10)
	v_mfma_f32_32x32x16_bf16 v[82:97], v[66:69], v[50:53], 0
	v_mul_f32_e64 v6, v6, v138
	v_mul_f32_e64 v7, v7, v138
	v_mul_f32_e64 v8, v8, v138
	v_mul_f32_e64 v9, v9, v138
	v_mul_f32_e64 v10, v10, v138
	v_mul_f32_e64 v11, v11, v138
	v_ashrrev_i32_e32 v173, 31, v172
	v_lshlrev_b32_e32 v1, 4, v1
	v_and_b32_e32 v154, 0xf0, v1
	v_mov_b32_e32 v155, v0
	s_waitcnt vmcnt(9)
	v_mfma_f32_32x32x16_bf16 v[66:81], v[70:73], v[50:53], 0
	v_mul_lo_u32 v1, v158, s45
	v_add_u32_e32 v1, 0, v1
	s_mov_b32 s14, 0
	s_waitcnt vmcnt(8)
	v_mfma_f32_32x32x16_bf16 v[82:97], v[102:105], v[58:61], v[82:97]
	global_load_dwordx4 v[62:65], v[134:135], off offset:2048
	global_load_dwordx4 v[102:105], v[134:135], off offset:3072
	s_waitcnt vmcnt(9)
	v_mfma_f32_32x32x16_bf16 v[66:81], v[106:109], v[58:61], v[66:81]
	v_cvt_pk_bf16_f32 v106, v34, v35
	v_cvt_pk_bf16_f32 v107, v36, v37
	v_cvt_pk_bf16_f32 v108, v38, v39
	v_cvt_pk_bf16_f32 v109, v40, v41
	global_load_dwordx4 v[34:37], v[136:137], off offset:1024
	global_load_dwordx4 v[38:41], v[136:137], off offset:2048
	s_waitcnt vmcnt(10)
	v_mfma_f32_32x32x16_bf16 v[82:97], v[110:113], v[106:109], v[82:97]
	v_cvt_pk_bf16_f32 v110, v42, v43
	v_cvt_pk_bf16_f32 v111, v44, v45
	global_load_dwordx4 v[42:45], v[136:137], off offset:3072
	v_cvt_pk_bf16_f32 v112, v46, v47
	v_or_b32_e32 v46, 16, v98
	v_ashrrev_i32_e32 v47, 31, v46
	v_lshlrev_b64 v[46:47], 10, v[46:47]
	v_lshl_add_u64 v[134:135], v[100:101], 0, v[46:47]
	s_waitcnt vmcnt(10)
	v_mfma_f32_32x32x16_bf16 v[66:81], v[114:117], v[106:109], v[66:81]
	v_cvt_pk_bf16_f32 v113, v48, v49
	v_cvt_pk_bf16_f32 v114, v18, v19
	v_cvt_pk_bf16_f32 v115, v20, v21
	v_cvt_pk_bf16_f32 v116, v22, v23
	v_cvt_pk_bf16_f32 v117, v24, v25
	global_load_dwordx4 v[18:21], v[134:135], off
	global_load_dwordx4 v[22:25], v[134:135], off offset:1024
	global_load_dwordx4 v[46:49], v[134:135], off offset:2048
	s_waitcnt vmcnt(12)
	v_mfma_f32_32x32x16_bf16 v[82:97], v[118:121], v[110:113], v[82:97]
	v_cvt_pk_bf16_f32 v118, v26, v27
	v_cvt_pk_bf16_f32 v119, v28, v29
	v_cvt_pk_bf16_f32 v120, v30, v31
	v_cvt_pk_bf16_f32 v121, v32, v33
	global_load_dwordx4 v[26:29], v[134:135], off offset:3072
	s_waitcnt vmcnt(12)
	v_mfma_f32_32x32x16_bf16 v[66:81], v[122:125], v[110:113], v[66:81]
	v_cvt_pk_bf16_f32 v122, v2, v3
	v_cvt_pk_bf16_f32 v123, v4, v5
	v_cvt_pk_bf16_f32 v124, v6, v7
	v_cvt_pk_bf16_f32 v125, v8, v9
	v_mul_f32_e64 v2, v12, v138
	v_mul_f32_e64 v3, v13, v138
	v_pk_mul_f32 v[4:5], v[14:15], v[138:139] op_sel_hi:[1,0]
	v_pk_mul_f32 v[6:7], v[16:17], v[138:139] op_sel_hi:[1,0]
	s_waitcnt vmcnt(11)
	v_mfma_f32_32x32x16_bf16 v[82:97], v[126:129], v[114:117], v[82:97]
	s_waitcnt vmcnt(10)
	v_mfma_f32_32x32x16_bf16 v[66:81], v[54:57], v[114:117], v[66:81]
	s_waitcnt vmcnt(9)
	v_mfma_f32_32x32x16_bf16 v[82:97], v[130:133], v[118:121], v[82:97]
	s_waitcnt vmcnt(6)
	v_mfma_f32_32x32x16_bf16 v[66:81], v[34:37], v[118:121], v[66:81]
	v_mfma_f32_32x32x16_bf16 v[82:97], v[62:65], v[122:125], v[82:97]
	v_cvt_pk_bf16_f32 v63, v2, v3
	v_add_co_u32_e32 v2, vcc, s37, v134
	v_cvt_pk_bf16_f32 v62, v10, v11
	s_nop 0
	v_addc_co_u32_e32 v3, vcc, 0, v135, vcc
	global_load_dwordx4 v[30:33], v[2:3], off
	global_load_dwordx4 v[34:37], v[2:3], off offset:1024
	s_waitcnt vmcnt(7)
	v_mfma_f32_32x32x16_bf16 v[66:81], v[38:41], v[122:125], v[66:81]
	v_cvt_pk_bf16_f32 v64, v4, v5
	v_cvt_pk_bf16_f32 v65, v6, v7
	s_waitcnt vmcnt(6)
	s_nop 0
	v_mfma_f32_32x32x16_bf16 v[66:81], v[42:45], v[62:65], v[66:81]
	global_load_dwordx4 v[38:41], v[2:3], off offset:2048
	global_load_dwordx4 v[42:45], v[2:3], off offset:3072
	s_waitcnt vmcnt(7)
	v_mfma_f32_32x32x16_bf16 v[2:17], v[18:21], v[50:53], 0
	v_or_b32_e32 v18, 24, v98
	v_ashrrev_i32_e32 v19, 31, v18
	v_lshlrev_b64 v[18:19], 10, v[18:19]
	v_lshl_add_u64 v[54:55], v[100:101], 0, v[18:19]
	global_load_dwordx4 v[18:21], v[54:55], off
	global_load_dwordx4 v[98:101], v[54:55], off offset:1024
	v_mfma_f32_32x32x16_bf16 v[82:97], v[102:105], v[62:65], v[82:97]
	global_load_dwordx4 v[102:105], v[54:55], off offset:2048
	global_load_dwordx4 v[126:129], v[54:55], off offset:3072
	s_waitcnt vmcnt(10)
	v_mfma_f32_32x32x16_bf16 v[2:17], v[22:25], v[58:61], v[2:17]
	v_add_co_u32_e32 v22, vcc, s37, v54
	v_mov_b32_e32 v24, s55
	s_nop 0
	v_addc_co_u32_e32 v23, vcc, 0, v55, vcc
	global_load_dwordx4 v[130:133], v[22:23], off
	global_load_dwordx4 v[134:137], v[22:23], off offset:1024
	global_load_dwordx4 v[138:141], v[22:23], off offset:2048
	global_load_dwordx4 v[142:145], v[22:23], off offset:3072
	s_waitcnt vmcnt(13)
	v_mfma_f32_32x32x16_bf16 v[2:17], v[46:49], v[106:109], v[2:17]
	v_lshlrev_b32_e32 v22, 5, v158
	v_and_b32_e32 v159, 0x60, v22
	v_lshlrev_b64 v[22:23], 12, v[172:173]
	v_bitop3_b32 v24, v159, s44, v24 bitop3:0xc8
	v_or3_b32 v22, v22, v24, v160
	v_lshlrev_b64 v[22:23], 8, v[22:23]
	s_waitcnt vmcnt(12)
	v_mfma_f32_32x32x16_bf16 v[2:17], v[26:29], v[110:113], v[2:17]
	s_waitcnt vmcnt(11)
	v_mfma_f32_32x32x16_bf16 v[2:17], v[30:33], v[114:117], v[2:17]
	s_waitcnt vmcnt(10)
	v_mfma_f32_32x32x16_bf16 v[2:17], v[34:37], v[118:121], v[2:17]
	v_lshl_add_u64 v[34:35], s[22:23], 0, v[22:23]
	v_lshl_add_u64 v[34:35], v[34:35], 0, v[154:155]
	s_waitcnt vmcnt(7)
	v_mfma_f32_32x32x16_bf16 v[18:33], v[18:21], v[50:53], 0
	global_load_dwordx4 v[146:149], v[34:35], off
	global_load_dwordx4 v[150:153], v[34:35], off offset:1024
	global_load_dwordx4 v[54:57], v[34:35], off offset:2048
	global_load_dwordx4 v[50:53], v[34:35], off offset:3072
	v_add_co_u32_e32 v34, vcc, s37, v34
	s_nop 1
	v_addc_co_u32_e32 v35, vcc, 0, v35, vcc
	s_waitcnt vmcnt(10)
	v_mfma_f32_32x32x16_bf16 v[18:33], v[98:101], v[58:61], v[18:33]
	v_mul_u32_u24_e32 v98, 0x110, v156
	v_lshlrev_b32_e32 v99, 5, v157
	v_cvt_pk_f16_f32 v58, v82, v83
	v_add3_u32 v82, v1, v98, v99
	v_cvt_pk_f16_f32 v59, v84, v85
	v_cvt_pk_f16_f32 v60, v86, v87
	v_cvt_pk_f16_f32 v61, v88, v89
	s_waitcnt vmcnt(9)
	v_mfma_f32_32x32x16_bf16 v[18:33], v[102:105], v[106:109], v[18:33]
	s_waitcnt vmcnt(8)
	v_mfma_f32_32x32x16_bf16 v[18:33], v[126:129], v[110:113], v[18:33]
	s_waitcnt vmcnt(7)
	v_mfma_f32_32x32x16_bf16 v[18:33], v[130:133], v[114:117], v[18:33]
	s_waitcnt vmcnt(6)
	v_mfma_f32_32x32x16_bf16 v[18:33], v[134:137], v[118:121], v[18:33]
	v_mfma_f32_32x32x16_bf16 v[2:17], v[38:41], v[122:125], v[2:17]
	s_waitcnt vmcnt(5)
	v_mfma_f32_32x32x16_bf16 v[18:33], v[138:141], v[122:125], v[18:33]
	v_mfma_f32_32x32x16_bf16 v[2:17], v[42:45], v[62:65], v[2:17]
	global_load_dwordx4 v[46:49], v[34:35], off
	global_load_dwordx4 v[42:45], v[34:35], off offset:1024
	global_load_dwordx4 v[38:41], v[34:35], off offset:2048
	s_nop 0
	global_load_dwordx4 v[34:37], v[34:35], off offset:3072
	ds_write_b128 v82, v[58:61] offset:49152
	v_cvt_pk_f16_f32 v58, v90, v91
	v_cvt_pk_f16_f32 v59, v92, v93
	v_cvt_pk_f16_f32 v60, v94, v95
	v_cvt_pk_f16_f32 v61, v96, v97
	ds_write_b128 v82, v[58:61] offset:49168
	s_waitcnt vmcnt(8)
	v_mfma_f32_32x32x16_bf16 v[18:33], v[142:145], v[62:65], v[18:33]
	v_cvt_pk_f16_f32 v2, v2, v3
	v_cvt_pk_f16_f32 v3, v4, v5
	v_cvt_pk_f16_f32 v4, v6, v7
	v_cvt_pk_f16_f32 v5, v8, v9
	ds_write_b128 v82, v[2:5] offset:49280
	v_cvt_pk_f16_f32 v2, v10, v11
	v_cvt_pk_f16_f32 v3, v12, v13
	v_cvt_pk_f16_f32 v4, v14, v15
	v_cvt_pk_f16_f32 v5, v16, v17
	ds_write_b128 v82, v[2:5] offset:49296
	s_nop 1
	v_cvt_pk_f16_f32 v2, v18, v19
	v_cvt_pk_f16_f32 v3, v20, v21
	v_cvt_pk_f16_f32 v4, v22, v23
	v_cvt_pk_f16_f32 v5, v24, v25
	v_cvt_pk_f16_f32 v58, v66, v67
	v_cvt_pk_f16_f32 v59, v68, v69
	v_cvt_pk_f16_f32 v60, v70, v71
	v_cvt_pk_f16_f32 v61, v72, v73
	ds_write_b128 v82, v[2:5] offset:49344
	v_cvt_pk_f16_f32 v2, v26, v27
	v_cvt_pk_f16_f32 v3, v28, v29
	v_cvt_pk_f16_f32 v4, v30, v31
	v_cvt_pk_f16_f32 v5, v32, v33
	ds_write_b128 v82, v[58:61] offset:49216
	v_cvt_pk_f16_f32 v58, v74, v75
	v_cvt_pk_f16_f32 v59, v76, v77
	v_cvt_pk_f16_f32 v60, v78, v79
	v_cvt_pk_f16_f32 v61, v80, v81
	ds_write_b128 v82, v[2:5] offset:49360
	v_mul_u32_u24_e32 v4, 0x110, v160
	ds_write_b128 v82, v[58:61] offset:49232
	v_add3_u32 v1, v1, v4, v154
	ds_read_b128 v[4:7], v1 offset:49152
	v_or3_b32 v2, v159, s55, v160
	v_mov_b32_e32 v3, v0
	v_lshlrev_b64 v[2:3], 12, v[2:3]
	v_lshlrev_b32_e32 v8, 7, v206
	v_lshl_add_u64 v[2:3], s[18:19], 0, v[2:3]
	v_ashrrev_i32_e32 v9, 31, v8
	v_lshl_add_u64 v[2:3], v[8:9], 1, v[2:3]
	ds_read_b128 v[8:11], v1 offset:50240
	s_waitcnt lgkmcnt(1)
	v_cvt_f32_f16_e32 v12, v4
	v_cvt_f32_f16_sdwa v13, v4 dst_sel:DWORD dst_unused:UNUSED_PAD src0_sel:WORD_1
	s_waitcnt vmcnt(7)
	v_lshlrev_b32_e32 v14, 16, v146
	v_and_b32_e32 v15, 0xffff0000, v146
	v_lshl_add_u64 v[2:3], v[2:3], 0, v[154:155]
	v_pk_mul_f32 v[12:13], v[14:15], v[12:13]
	v_cvt_f32_f16_e32 v14, v5
	v_cvt_f32_f16_sdwa v15, v5 dst_sel:DWORD dst_unused:UNUSED_PAD src0_sel:WORD_1
	v_cvt_pk_bf16_f32 v4, v12, v13
	v_lshlrev_b32_e32 v12, 16, v147
	v_and_b32_e32 v13, 0xffff0000, v147
	v_pk_mul_f32 v[12:13], v[12:13], v[14:15]
	v_cvt_f32_f16_e32 v14, v6
	v_cvt_f32_f16_sdwa v15, v6 dst_sel:DWORD dst_unused:UNUSED_PAD src0_sel:WORD_1
	v_cvt_pk_bf16_f32 v5, v12, v13
	v_lshlrev_b32_e32 v12, 16, v148
	v_and_b32_e32 v13, 0xffff0000, v148
	v_pk_mul_f32 v[12:13], v[12:13], v[14:15]
	v_cvt_f32_f16_e32 v14, v7
	v_cvt_f32_f16_sdwa v15, v7 dst_sel:DWORD dst_unused:UNUSED_PAD src0_sel:WORD_1
	v_cvt_pk_bf16_f32 v6, v12, v13
	v_lshlrev_b32_e32 v12, 16, v149
	v_and_b32_e32 v13, 0xffff0000, v149
	v_pk_mul_f32 v[12:13], v[12:13], v[14:15]
	v_add_co_u32_e32 v16, vcc, s16, v2
	v_cvt_pk_bf16_f32 v7, v12, v13
	global_store_dwordx4 v[2:3], v[4:7], off
	s_waitcnt lgkmcnt(0)
	v_cvt_f32_f16_e32 v12, v8
	v_cvt_f32_f16_sdwa v13, v8 dst_sel:DWORD dst_unused:UNUSED_PAD src0_sel:WORD_1
	v_cvt_f32_f16_e32 v6, v9
	v_cvt_f32_f16_sdwa v7, v9 dst_sel:DWORD dst_unused:UNUSED_PAD src0_sel:WORD_1
	s_waitcnt vmcnt(7)
	v_lshlrev_b32_e32 v8, 16, v151
	v_and_b32_e32 v9, 0xffff0000, v151
	v_lshlrev_b32_e32 v4, 16, v150
	v_pk_mul_f32 v[6:7], v[8:9], v[6:7]
	v_cvt_f32_f16_e32 v8, v10
	v_cvt_f32_f16_sdwa v9, v10 dst_sel:DWORD dst_unused:UNUSED_PAD src0_sel:WORD_1
	v_and_b32_e32 v5, 0xffff0000, v150
	v_pk_mul_f32 v[4:5], v[4:5], v[12:13]
	v_lshlrev_b32_e32 v10, 16, v153
	v_cvt_pk_bf16_f32 v4, v4, v5
	v_cvt_pk_bf16_f32 v5, v6, v7
	v_lshlrev_b32_e32 v6, 16, v152
	v_and_b32_e32 v7, 0xffff0000, v152
	v_pk_mul_f32 v[6:7], v[6:7], v[8:9]
	v_cvt_f32_f16_e32 v8, v11
	v_cvt_f32_f16_sdwa v9, v11 dst_sel:DWORD dst_unused:UNUSED_PAD src0_sel:WORD_1
	v_and_b32_e32 v11, 0xffff0000, v153
	v_cvt_pk_bf16_f32 v6, v6, v7
	v_addc_co_u32_e32 v17, vcc, 0, v3, vcc
	v_pk_mul_f32 v[8:9], v[10:11], v[8:9]
	ds_read_b128 v[12:15], v1 offset:52416
	v_cvt_pk_bf16_f32 v7, v8, v9
	ds_read_b128 v[8:11], v1 offset:51328
	global_store_dwordx4 v[16:17], v[4:7], off
	s_waitcnt lgkmcnt(0)
	v_cvt_f32_f16_e32 v18, v8
	v_cvt_f32_f16_e32 v6, v9
	v_cvt_f32_f16_sdwa v7, v9 dst_sel:DWORD dst_unused:UNUSED_PAD src0_sel:WORD_1
	v_cvt_f32_f16_sdwa v19, v8 dst_sel:DWORD dst_unused:UNUSED_PAD src0_sel:WORD_1
	s_waitcnt vmcnt(7)
	v_lshlrev_b32_e32 v8, 16, v55
	v_and_b32_e32 v9, 0xffff0000, v55
	v_pk_mul_f32 v[6:7], v[8:9], v[6:7]
	v_cvt_f32_f16_e32 v8, v10
	v_cvt_f32_f16_sdwa v9, v10 dst_sel:DWORD dst_unused:UNUSED_PAD src0_sel:WORD_1
	v_lshlrev_b32_e32 v4, 16, v54
	v_and_b32_e32 v5, 0xffff0000, v54
	v_pk_mul_f32 v[4:5], v[4:5], v[18:19]
	v_lshlrev_b32_e32 v10, 16, v57
	v_cvt_pk_bf16_f32 v4, v4, v5
	v_cvt_pk_bf16_f32 v5, v6, v7
	v_lshlrev_b32_e32 v6, 16, v56
	v_and_b32_e32 v7, 0xffff0000, v56
	v_pk_mul_f32 v[6:7], v[6:7], v[8:9]
	v_cvt_f32_f16_e32 v8, v11
	v_cvt_f32_f16_sdwa v9, v11 dst_sel:DWORD dst_unused:UNUSED_PAD src0_sel:WORD_1
	v_and_b32_e32 v11, 0xffff0000, v57
	v_cvt_pk_bf16_f32 v6, v6, v7
	v_pk_mul_f32 v[8:9], v[10:11], v[8:9]
	s_nop 0
	v_cvt_pk_bf16_f32 v7, v8, v9
	v_add_co_u32_e32 v8, vcc, s41, v2
	v_cvt_f32_f16_e32 v10, v12
	s_nop 0
	v_addc_co_u32_e32 v9, vcc, 0, v3, vcc
	global_store_dwordx4 v[8:9], v[4:7], off
	v_cvt_f32_f16_sdwa v11, v12 dst_sel:DWORD dst_unused:UNUSED_PAD src0_sel:WORD_1
	s_waitcnt vmcnt(7)
	v_lshlrev_b32_e32 v8, 16, v51
	v_cvt_f32_f16_e32 v6, v13
	v_cvt_f32_f16_sdwa v7, v13 dst_sel:DWORD dst_unused:UNUSED_PAD src0_sel:WORD_1
	v_and_b32_e32 v9, 0xffff0000, v51
	v_lshlrev_b32_e32 v4, 16, v50
	v_and_b32_e32 v5, 0xffff0000, v50
	v_pk_mul_f32 v[6:7], v[8:9], v[6:7]
	v_cvt_f32_f16_e32 v8, v14
	v_cvt_f32_f16_sdwa v9, v14 dst_sel:DWORD dst_unused:UNUSED_PAD src0_sel:WORD_1
	v_pk_mul_f32 v[4:5], v[4:5], v[10:11]
	v_lshlrev_b32_e32 v10, 16, v53
	v_cvt_pk_bf16_f32 v4, v4, v5
	v_cvt_pk_bf16_f32 v5, v6, v7
	v_lshlrev_b32_e32 v6, 16, v52
	v_and_b32_e32 v7, 0xffff0000, v52
	v_pk_mul_f32 v[6:7], v[6:7], v[8:9]
	v_cvt_f32_f16_e32 v8, v15
	v_cvt_f32_f16_sdwa v9, v15 dst_sel:DWORD dst_unused:UNUSED_PAD src0_sel:WORD_1
	v_and_b32_e32 v11, 0xffff0000, v53
	v_cvt_pk_bf16_f32 v6, v6, v7
	v_add_co_u32_e32 v16, vcc, s50, v2
	v_pk_mul_f32 v[8:9], v[10:11], v[8:9]
	s_nop 0
	v_addc_co_u32_e32 v17, vcc, 0, v3, vcc
	v_cvt_pk_bf16_f32 v7, v8, v9
	ds_read_b128 v[8:11], v1 offset:53504
	ds_read_b128 v[12:15], v1 offset:54592
	global_store_dwordx4 v[16:17], v[4:7], off
	s_waitcnt lgkmcnt(1)
	v_cvt_f32_f16_e32 v18, v8
	v_cvt_f32_f16_e32 v6, v9
	v_cvt_f32_f16_sdwa v7, v9 dst_sel:DWORD dst_unused:UNUSED_PAD src0_sel:WORD_1
	v_cvt_f32_f16_sdwa v19, v8 dst_sel:DWORD dst_unused:UNUSED_PAD src0_sel:WORD_1
	s_waitcnt vmcnt(7)
	v_lshlrev_b32_e32 v8, 16, v47
	v_and_b32_e32 v9, 0xffff0000, v47
	v_pk_mul_f32 v[6:7], v[8:9], v[6:7]
	v_cvt_f32_f16_e32 v8, v10
	v_cvt_f32_f16_sdwa v9, v10 dst_sel:DWORD dst_unused:UNUSED_PAD src0_sel:WORD_1
	v_lshlrev_b32_e32 v4, 16, v46
	v_and_b32_e32 v5, 0xffff0000, v46
	v_pk_mul_f32 v[4:5], v[4:5], v[18:19]
	v_lshlrev_b32_e32 v10, 16, v49
	v_cvt_pk_bf16_f32 v4, v4, v5
	v_cvt_pk_bf16_f32 v5, v6, v7
	v_lshlrev_b32_e32 v6, 16, v48
	v_and_b32_e32 v7, 0xffff0000, v48
	v_pk_mul_f32 v[6:7], v[6:7], v[8:9]
	v_cvt_f32_f16_e32 v8, v11
	v_cvt_f32_f16_sdwa v9, v11 dst_sel:DWORD dst_unused:UNUSED_PAD src0_sel:WORD_1
	v_and_b32_e32 v11, 0xffff0000, v49
	v_cvt_pk_bf16_f32 v6, v6, v7
	v_pk_mul_f32 v[8:9], v[10:11], v[8:9]
	s_nop 0
	v_cvt_pk_bf16_f32 v7, v8, v9
	v_add_co_u32_e32 v8, vcc, s51, v2
	s_waitcnt lgkmcnt(0)
	v_cvt_f32_f16_e32 v10, v12
	v_addc_co_u32_e32 v9, vcc, 0, v3, vcc
	global_store_dwordx4 v[8:9], v[4:7], off
	v_cvt_f32_f16_sdwa v11, v12 dst_sel:DWORD dst_unused:UNUSED_PAD src0_sel:WORD_1
	s_waitcnt vmcnt(7)
	v_lshlrev_b32_e32 v8, 16, v43
	v_cvt_f32_f16_e32 v6, v13
	v_cvt_f32_f16_sdwa v7, v13 dst_sel:DWORD dst_unused:UNUSED_PAD src0_sel:WORD_1
	v_and_b32_e32 v9, 0xffff0000, v43
	v_lshlrev_b32_e32 v4, 16, v42
	v_and_b32_e32 v5, 0xffff0000, v42
	v_pk_mul_f32 v[6:7], v[8:9], v[6:7]
	v_cvt_f32_f16_e32 v8, v14
	v_cvt_f32_f16_sdwa v9, v14 dst_sel:DWORD dst_unused:UNUSED_PAD src0_sel:WORD_1
	v_pk_mul_f32 v[4:5], v[4:5], v[10:11]
	v_lshlrev_b32_e32 v10, 16, v45
	v_cvt_pk_bf16_f32 v4, v4, v5
	v_cvt_pk_bf16_f32 v5, v6, v7
	v_lshlrev_b32_e32 v6, 16, v44
	v_and_b32_e32 v7, 0xffff0000, v44
	v_pk_mul_f32 v[6:7], v[6:7], v[8:9]
	v_cvt_f32_f16_e32 v8, v15
	v_cvt_f32_f16_sdwa v9, v15 dst_sel:DWORD dst_unused:UNUSED_PAD src0_sel:WORD_1
	v_and_b32_e32 v11, 0xffff0000, v45
	v_cvt_pk_bf16_f32 v6, v6, v7
	v_add_co_u32_e32 v16, vcc, s52, v2
	v_pk_mul_f32 v[8:9], v[10:11], v[8:9]
	s_nop 0
	v_addc_co_u32_e32 v17, vcc, 0, v3, vcc
	v_cvt_pk_bf16_f32 v7, v8, v9
	ds_read_b128 v[8:11], v1 offset:55680
	ds_read_b128 v[12:15], v1 offset:56768
	global_store_dwordx4 v[16:17], v[4:7], off
	s_waitcnt lgkmcnt(1)
	v_cvt_f32_f16_e32 v18, v8
	v_cvt_f32_f16_e32 v6, v9
	v_cvt_f32_f16_sdwa v7, v9 dst_sel:DWORD dst_unused:UNUSED_PAD src0_sel:WORD_1
	v_cvt_f32_f16_sdwa v19, v8 dst_sel:DWORD dst_unused:UNUSED_PAD src0_sel:WORD_1
	s_waitcnt vmcnt(7)
	v_lshlrev_b32_e32 v8, 16, v39
	v_and_b32_e32 v9, 0xffff0000, v39
	v_pk_mul_f32 v[6:7], v[8:9], v[6:7]
	v_cvt_f32_f16_e32 v8, v10
	v_cvt_f32_f16_sdwa v9, v10 dst_sel:DWORD dst_unused:UNUSED_PAD src0_sel:WORD_1
	v_lshlrev_b32_e32 v4, 16, v38
	v_and_b32_e32 v5, 0xffff0000, v38
	v_pk_mul_f32 v[4:5], v[4:5], v[18:19]
	v_lshlrev_b32_e32 v10, 16, v41
	v_cvt_pk_bf16_f32 v4, v4, v5
	v_cvt_pk_bf16_f32 v5, v6, v7
	v_lshlrev_b32_e32 v6, 16, v40
	v_and_b32_e32 v7, 0xffff0000, v40
	v_pk_mul_f32 v[6:7], v[6:7], v[8:9]
	v_cvt_f32_f16_e32 v8, v11
	v_cvt_f32_f16_sdwa v9, v11 dst_sel:DWORD dst_unused:UNUSED_PAD src0_sel:WORD_1
	v_and_b32_e32 v11, 0xffff0000, v41
	v_cvt_pk_bf16_f32 v6, v6, v7
	v_pk_mul_f32 v[8:9], v[10:11], v[8:9]
	s_nop 0
	v_cvt_pk_bf16_f32 v7, v8, v9
	v_add_co_u32_e32 v8, vcc, s53, v2
	s_waitcnt lgkmcnt(0)
	v_cvt_f32_f16_e32 v10, v12
	v_addc_co_u32_e32 v9, vcc, 0, v3, vcc
	global_store_dwordx4 v[8:9], v[4:7], off
	v_cvt_f32_f16_sdwa v11, v12 dst_sel:DWORD dst_unused:UNUSED_PAD src0_sel:WORD_1
	s_waitcnt vmcnt(7)
	v_lshlrev_b32_e32 v8, 16, v35
	v_cvt_f32_f16_e32 v6, v13
	v_cvt_f32_f16_sdwa v7, v13 dst_sel:DWORD dst_unused:UNUSED_PAD src0_sel:WORD_1
	v_and_b32_e32 v9, 0xffff0000, v35
	v_lshlrev_b32_e32 v4, 16, v34
	v_and_b32_e32 v5, 0xffff0000, v34
	v_pk_mul_f32 v[6:7], v[8:9], v[6:7]
	v_cvt_f32_f16_e32 v8, v14
	v_cvt_f32_f16_sdwa v9, v14 dst_sel:DWORD dst_unused:UNUSED_PAD src0_sel:WORD_1
	v_pk_mul_f32 v[4:5], v[4:5], v[10:11]
	v_lshlrev_b32_e32 v10, 16, v37
	v_cvt_pk_bf16_f32 v4, v4, v5
	v_cvt_pk_bf16_f32 v5, v6, v7
	v_lshlrev_b32_e32 v6, 16, v36
	v_and_b32_e32 v7, 0xffff0000, v36
	v_pk_mul_f32 v[6:7], v[6:7], v[8:9]
	v_cvt_f32_f16_e32 v8, v15
	v_cvt_f32_f16_sdwa v9, v15 dst_sel:DWORD dst_unused:UNUSED_PAD src0_sel:WORD_1
	v_and_b32_e32 v11, 0xffff0000, v37
	v_add_co_u32_e32 v2, vcc, 0x1c000, v2
	v_pk_mul_f32 v[8:9], v[10:11], v[8:9]
	v_cvt_pk_bf16_f32 v6, v6, v7
	v_cvt_pk_bf16_f32 v7, v8, v9
	v_addc_co_u32_e32 v3, vcc, 0, v3, vcc
	global_store_dwordx4 v[2:3], v[4:7], off
